# P6 conv epilogue: the wait in front of the conv-coefficient LDS writes leaves the four just-issued edge-row stores in flight (vmcnt(4) instead of vmcnt(0))
# speedup vs baseline: 1.0137x; 1.0011x over previous
; #define LAS __attribute__((address_space(3)))
; __device__ __forceinline__ float sigmoidf_(float x) { return __builtin_amdgcn_rcpf(1.0f + __expf(-x)); }
;     __device__ __forceinline__ void conv_rows(const f32x4 curg, const f32x4 curv, f32x4 (&q1)[2], f32x4 (&q2)[2], const LAS float* cp, bf16_t* dst, const bool upd) const {
;         f32x4 uc[2];
; #pragma unroll
;         for (int bj = 0; bj < 2; ++bj) {
;             const f32x4 c0 = *(const LAS f32x4*)(cp + bj * 32), c1 = *(const LAS f32x4*)(cp + bj * 32 + 64), c2 = *(const LAS f32x4*)(cp + bj * 32 + 128), bb = *(const LAS f32x4*)(cp + bj * 32 + 192);
;             const f32x4 cur = bj ? curv : curg;
; #pragma unroll
;             for (int e = 0; e < 4; ++e) {
;                 const float p1 = dpp_shr1(q1[bj][e], cur[e]), p2 = dpp_shr2(q2[bj][e], cur[e]);
;                 uc[bj][e] = bb[e] + c0[e] * p2 + c1[e] * p1 + c2[e] * cur[e];
;                 if (upd) { q1[bj][e] = dpp_ror1(cur[e]); q2[bj][e] = dpp_ror2(cur[e]); }
;             }
;         }
;         u32x2 w;
;         { const float a0 = uc[0][0] * sigmoidf_(uc[0][0]) * uc[1][0], a1 = uc[0][1] * sigmoidf_(uc[0][1]) * uc[1][1];
;           const float a2 = uc[0][2] * sigmoidf_(uc[0][2]) * uc[1][2], a3 = uc[0][3] * sigmoidf_(uc[0][3]) * uc[1][3];
;           w.x = cvt_pk_bf16(a0, a1); w.y = cvt_pk_bf16(a2, a3); }
;         *(u32x2*)dst = w;
;     __device__ __forceinline__ void operator()(f32x4 (&acc)[2][2][4][2], const Unit& u, int wr, int wc, int fr, int fq) const {
;     ...
;         LAS float* myc = cws + wv * 256;
; #pragma unroll
;         for (int i = 0; i < 4; ++i) myc[i * 64 + ln] = cwr[i];
;         asm volatile("s_waitcnt lgkmcnt(0)" ::: "memory");
; #pragma unroll
;         for (int n = 0; n < 2; ++n) {
;             const int jcol = u.pn * HALF + cl0 + n * 16; const LAS float* cp = myc + 16 * n + 4 * fq;
; #pragma unroll
;             for (int ai = 0; ai < 2; ++ai) {
;                 f32x4 q1[2], q2[2];
; #pragma unroll
;                 for (int bj = 0; bj < 2; ++bj)
; #pragma unroll
;                     for (int e = 0; e < 4; ++e) { q1[bj][e] = dpp_ror1(acc[ai][bj][0][n][e]); q2[bj][e] = dpp_ror2(acc[ai][bj][0][n][e]); }
; #pragma unroll
;                 for (int m = 1; m < 4; ++m) conv_rows(acc[ai][0][m][n], acc[ai][1][m][n], q1, q2, cp, act + (size_t)(rowt + ai * HALF + m * 16) * FF + jcol, m < 3);
.Lp6_ue_done:
	s_or_b64 exec, exec, s[2:3]
	v_lshl_add_u32 v155, v164, 2, s60
	s_waitcnt vmcnt(4)
	ds_write2st64_b32 v155, v165, v166 offset1:1
	ds_write2st64_b32 v155, v167, v168 offset0:2 offset1:3
	v_lshl_add_u32 v153, v153, 2, s60
	v_mul_lo_u32 v155, v152, s69
	v_lshl_add_u32 v155, v154, 1, v155
	v_add_u32_e32 v155, s15, v155
	v_cmp_eq_u32_e64 s[42:43], 1, v179
	s_waitcnt lgkmcnt(0)
	ds_read_b128 v[188:191], v153
	ds_read_b128 v[192:195], v153 offset:128
	ds_read_b128 v[196:199], v153 offset:256
	ds_read_b128 v[200:203], v153 offset:384
	ds_read_b128 v[204:207], v153 offset:512
	ds_read_b128 v[210:213], v153 offset:640
	ds_read_b128 v[214:217], v153 offset:768
	ds_read_b128 v[218:221], v153 offset:896
	v_mov_b32_dpp v222, v128 row_ror:1 row_mask:0xf bank_mask:0xf
	v_mov_b32_dpp v223, v129 row_ror:1 row_mask:0xf bank_mask:0xf
	v_mov_b32_dpp v224, v130 row_ror:1 row_mask:0xf bank_mask:0xf
	v_mov_b32_dpp v225, v131 row_ror:1 row_mask:0xf bank_mask:0xf
	v_mov_b32_dpp v230, v128 row_ror:2 row_mask:0xf bank_mask:0xf
	v_mov_b32_dpp v231, v129 row_ror:2 row_mask:0xf bank_mask:0xf
	v_mov_b32_dpp v232, v130 row_ror:2 row_mask:0xf bank_mask:0xf
	v_mov_b32_dpp v233, v131 row_ror:2 row_mask:0xf bank_mask:0xf
	v_mov_b32_dpp v226, v12 row_ror:1 row_mask:0xf bank_mask:0xf
	v_mov_b32_dpp v227, v13 row_ror:1 row_mask:0xf bank_mask:0xf
	v_mov_b32_dpp v228, v14 row_ror:1 row_mask:0xf bank_mask:0xf
	v_mov_b32_dpp v229, v15 row_ror:1 row_mask:0xf bank_mask:0xf
	v_mov_b32_dpp v108, v12 row_ror:2 row_mask:0xf bank_mask:0xf
	v_mov_b32_dpp v109, v13 row_ror:2 row_mask:0xf bank_mask:0xf
	v_mov_b32_dpp v110, v14 row_ror:2 row_mask:0xf bank_mask:0xf
	v_mov_b32_dpp v111, v15 row_ror:2 row_mask:0xf bank_mask:0xf
	s_waitcnt lgkmcnt(0)
	v_mov_b32_dpp v222, v116 row_shr:1 row_mask:0xf bank_mask:0xf
	v_mov_b32_dpp v223, v117 row_shr:1 row_mask:0xf bank_mask:0xf
	v_mov_b32_dpp v224, v118 row_shr:1 row_mask:0xf bank_mask:0xf
	v_mov_b32_dpp v225, v119 row_shr:1 row_mask:0xf bank_mask:0xf
	v_mov_b32_dpp v230, v116 row_shr:2 row_mask:0xf bank_mask:0xf
	v_mov_b32_dpp v231, v117 row_shr:2 row_mask:0xf bank_mask:0xf
	v_mov_b32_dpp v232, v118 row_shr:2 row_mask:0xf bank_mask:0xf
	v_mov_b32_dpp v233, v119 row_shr:2 row_mask:0xf bank_mask:0xf
	v_mov_b32_dpp v226, v100 row_shr:1 row_mask:0xf bank_mask:0xf
	v_mov_b32_dpp v227, v101 row_shr:1 row_mask:0xf bank_mask:0xf
	v_mov_b32_dpp v228, v102 row_shr:1 row_mask:0xf bank_mask:0xf
	v_mov_b32_dpp v229, v103 row_shr:1 row_mask:0xf bank_mask:0xf
	v_mov_b32_dpp v108, v100 row_shr:2 row_mask:0xf bank_mask:0xf
	v_mov_b32_dpp v109, v101 row_shr:2 row_mask:0xf bank_mask:0xf
	v_mov_b32_dpp v110, v102 row_shr:2 row_mask:0xf bank_mask:0xf
	v_mov_b32_dpp v111, v103 row_shr:2 row_mask:0xf bank_mask:0xf
	v_mov_b32_dpp v132, v116 row_ror:1 row_mask:0xf bank_mask:0xf
	v_mov_b32_dpp v133, v117 row_ror:1 row_mask:0xf bank_mask:0xf
	v_mov_b32_dpp v134, v118 row_ror:1 row_mask:0xf bank_mask:0xf
	v_mov_b32_dpp v135, v119 row_ror:1 row_mask:0xf bank_mask:0xf
	v_mov_b32_dpp v156, v116 row_ror:2 row_mask:0xf bank_mask:0xf
	v_mov_b32_dpp v157, v117 row_ror:2 row_mask:0xf bank_mask:0xf
	v_mov_b32_dpp v158, v118 row_ror:2 row_mask:0xf bank_mask:0xf
	v_mov_b32_dpp v159, v119 row_ror:2 row_mask:0xf bank_mask:0xf
	v_mov_b32_dpp v136, v100 row_ror:1 row_mask:0xf bank_mask:0xf
	v_mov_b32_dpp v137, v101 row_ror:1 row_mask:0xf bank_mask:0xf
	v_mov_b32_dpp v138, v102 row_ror:1 row_mask:0xf bank_mask:0xf
	v_mov_b32_dpp v139, v103 row_ror:1 row_mask:0xf bank_mask:0xf
	v_mov_b32_dpp v160, v100 row_ror:2 row_mask:0xf bank_mask:0xf
	v_mov_b32_dpp v161, v101 row_ror:2 row_mask:0xf bank_mask:0xf
	v_mov_b32_dpp v162, v102 row_ror:2 row_mask:0xf bank_mask:0xf
	v_mov_b32_dpp v163, v103 row_ror:2 row_mask:0xf bank_mask:0xf
	v_pk_fma_f32 v[164:165], v[188:189], v[230:231], v[214:215]
	v_pk_fma_f32 v[166:167], v[190:191], v[232:233], v[216:217]
	v_pk_fma_f32 v[164:165], v[196:197], v[222:223], v[164:165]
	v_pk_fma_f32 v[166:167], v[198:199], v[224:225], v[166:167]
	v_pk_fma_f32 v[164:165], v[116:117], v[204:205], v[164:165]
	v_pk_fma_f32 v[166:167], v[118:119], v[206:207], v[166:167]
	v_pk_fma_f32 v[168:169], v[192:193], v[108:109], v[218:219]
	v_pk_fma_f32 v[170:171], v[194:195], v[110:111], v[220:221]
	v_pk_fma_f32 v[168:169], v[200:201], v[226:227], v[168:169]
	v_pk_fma_f32 v[170:171], v[202:203], v[228:229], v[170:171]
	v_pk_fma_f32 v[168:169], v[100:101], v[210:211], v[168:169]
	v_pk_fma_f32 v[170:171], v[102:103], v[212:213], v[170:171]
	v_pk_mul_f32 v[222:223], v[164:165], s[28:29] op_sel_hi:[1,0]
	v_pk_mul_f32 v[224:225], v[166:167], s[28:29] op_sel_hi:[1,0]
	v_exp_f32_e32 v222, v222
	v_exp_f32_e32 v223, v223
	v_exp_f32_e32 v224, v224
	v_exp_f32_e32 v225, v225
	v_pk_add_f32 v[222:223], v[222:223], s[28:29] op_sel:[0,1] op_sel_hi:[1,1]
	v_pk_add_f32 v[224:225], v[224:225], s[28:29] op_sel:[0,1] op_sel_hi:[1,1]
	v_rcp_f32_e32 v222, v222
	v_rcp_f32_e32 v223, v223
	v_rcp_f32_e32 v224, v224
	v_rcp_f32_e32 v225, v225
	v_pk_mul_f32 v[164:165], v[164:165], v[222:223]
	v_pk_mul_f32 v[166:167], v[166:167], v[224:225]
	v_pk_mul_f32 v[164:165], v[164:165], v[168:169]
	v_pk_mul_f32 v[166:167], v[166:167], v[170:171]
	v_cvt_pk_bf16_f32 v164, v164, v165
	v_cvt_pk_bf16_f32 v165, v166, v167
	v_add_u32_e32 v181, 0x2c000, v155
	global_store_dwordx2 v181, v[164:165], s[0:1]
	v_mov_b32_dpp v132, v104 row_shr:1 row_mask:0xf bank_mask:0xf
	v_mov_b32_dpp v133, v105 row_shr:1 row_mask:0xf bank_mask:0xf
	v_mov_b32_dpp v134, v106 row_shr:1 row_mask:0xf bank_mask:0xf
	v_mov_b32_dpp v135, v107 row_shr:1 row_mask:0xf bank_mask:0xf
	v_mov_b32_dpp v156, v104 row_shr:2 row_mask:0xf bank_mask:0xf
; #define LAS __attribute__((address_space(3)))
; __device__ __forceinline__ unsigned cvt_pk_bf16(float lo, float hi) { unsigned r; asm volatile("v_cvt_pk_bf16_f32 %0, %1, %2" : "=v"(r) : "v"(lo), "v"(hi)); return r; }
; __device__ __forceinline__ float sigmoidf_(float x) { return __builtin_amdgcn_rcpf(1.0f + __expf(-x)); }
; __device__ __forceinline__ float dpp_ror1(float v) { return __int_as_float(__builtin_amdgcn_update_dpp(0, __float_as_int(v), 0x121, 0xf, 0xf, false)); }
;     __device__ __forceinline__ void conv_rows(const f32x4 curg, const f32x4 curv, f32x4 (&q1)[2], f32x4 (&q2)[2], const LAS float* cp, bf16_t* dst, const bool upd) const {
;         f32x4 uc[2];
; #pragma unroll
;         for (int bj = 0; bj < 2; ++bj) {
;             const f32x4 c0 = *(const LAS f32x4*)(cp + bj * 32), c1 = *(const LAS f32x4*)(cp + bj * 32 + 64), c2 = *(const LAS f32x4*)(cp + bj * 32 + 128), bb = *(const LAS f32x4*)(cp + bj * 32 + 192);
;             const f32x4 cur = bj ? curv : curg;
; #pragma unroll
;             for (int e = 0; e < 4; ++e) {
;                 const float p1 = dpp_shr1(q1[bj][e], cur[e]), p2 = dpp_shr2(q2[bj][e], cur[e]);
;                 uc[bj][e] = bb[e] + c0[e] * p2 + c1[e] * p1 + c2[e] * cur[e];
;                 if (upd) { q1[bj][e] = dpp_ror1(cur[e]); q2[bj][e] = dpp_ror2(cur[e]); }
;             }
;         }
;         u32x2 w;
;         { const float a0 = uc[0][0] * sigmoidf_(uc[0][0]) * uc[1][0], a1 = uc[0][1] * sigmoidf_(uc[0][1]) * uc[1][1];
;           const float a2 = uc[0][2] * sigmoidf_(uc[0][2]) * uc[1][2], a3 = uc[0][3] * sigmoidf_(uc[0][3]) * uc[1][3];
;           w.x = cvt_pk_bf16(a0, a1); w.y = cvt_pk_bf16(a2, a3); }
;         *(u32x2*)dst = w;
;     __device__ __forceinline__ void operator()(f32x4 (&acc)[2][2][4][2], const Unit& u, int wr, int wc, int fr, int fq) const {
;     ...
;                 f32x4 q1[2], q2[2];
; #pragma unroll
;                 for (int bj = 0; bj < 2; ++bj)
; #pragma unroll
;                     for (int e = 0; e < 4; ++e) { q1[bj][e] = dpp_ror1(acc[ai][bj][0][n][e]); q2[bj][e] = dpp_ror2(acc[ai][bj][0][n][e]); }
; #pragma unroll
;                 for (int m = 1; m < 4; ++m) conv_rows(acc[ai][0][m][n], acc[ai][1][m][n], q1, q2, cp, act + (size_t)(rowt + ai * HALF + m * 16) * FF + jcol, m < 3);
	v_mov_b32_dpp v157, v105 row_shr:2 row_mask:0xf bank_mask:0xf
	v_mov_b32_dpp v158, v106 row_shr:2 row_mask:0xf bank_mask:0xf
	v_mov_b32_dpp v159, v107 row_shr:2 row_mask:0xf bank_mask:0xf
	v_mov_b32_dpp v136, v84 row_shr:1 row_mask:0xf bank_mask:0xf
	v_mov_b32_dpp v137, v85 row_shr:1 row_mask:0xf bank_mask:0xf
	v_mov_b32_dpp v138, v86 row_shr:1 row_mask:0xf bank_mask:0xf
	v_mov_b32_dpp v139, v87 row_shr:1 row_mask:0xf bank_mask:0xf
	v_mov_b32_dpp v160, v84 row_shr:2 row_mask:0xf bank_mask:0xf
	v_mov_b32_dpp v161, v85 row_shr:2 row_mask:0xf bank_mask:0xf
	v_mov_b32_dpp v162, v86 row_shr:2 row_mask:0xf bank_mask:0xf
	v_mov_b32_dpp v163, v87 row_shr:2 row_mask:0xf bank_mask:0xf
	v_mov_b32_dpp v222, v104 row_ror:1 row_mask:0xf bank_mask:0xf
	v_mov_b32_dpp v223, v105 row_ror:1 row_mask:0xf bank_mask:0xf
	v_mov_b32_dpp v224, v106 row_ror:1 row_mask:0xf bank_mask:0xf
	v_mov_b32_dpp v225, v107 row_ror:1 row_mask:0xf bank_mask:0xf
	v_mov_b32_dpp v230, v104 row_ror:2 row_mask:0xf bank_mask:0xf
	v_mov_b32_dpp v231, v105 row_ror:2 row_mask:0xf bank_mask:0xf
	v_mov_b32_dpp v232, v106 row_ror:2 row_mask:0xf bank_mask:0xf
	v_mov_b32_dpp v233, v107 row_ror:2 row_mask:0xf bank_mask:0xf
	v_mov_b32_dpp v226, v84 row_ror:1 row_mask:0xf bank_mask:0xf
	v_mov_b32_dpp v227, v85 row_ror:1 row_mask:0xf bank_mask:0xf
	v_mov_b32_dpp v228, v86 row_ror:1 row_mask:0xf bank_mask:0xf
	v_mov_b32_dpp v229, v87 row_ror:1 row_mask:0xf bank_mask:0xf
	v_mov_b32_dpp v108, v84 row_ror:2 row_mask:0xf bank_mask:0xf
	v_mov_b32_dpp v109, v85 row_ror:2 row_mask:0xf bank_mask:0xf
	v_mov_b32_dpp v110, v86 row_ror:2 row_mask:0xf bank_mask:0xf
	v_mov_b32_dpp v111, v87 row_ror:2 row_mask:0xf bank_mask:0xf
	v_pk_fma_f32 v[164:165], v[188:189], v[156:157], v[214:215]
	v_pk_fma_f32 v[166:167], v[190:191], v[158:159], v[216:217]
	v_pk_fma_f32 v[164:165], v[196:197], v[132:133], v[164:165]
	v_pk_fma_f32 v[166:167], v[198:199], v[134:135], v[166:167]
	v_pk_fma_f32 v[164:165], v[104:105], v[204:205], v[164:165]
	v_pk_fma_f32 v[166:167], v[106:107], v[206:207], v[166:167]
	v_pk_fma_f32 v[168:169], v[192:193], v[160:161], v[218:219]
	v_pk_fma_f32 v[170:171], v[194:195], v[162:163], v[220:221]
	v_pk_fma_f32 v[168:169], v[200:201], v[136:137], v[168:169]
	v_pk_fma_f32 v[170:171], v[202:203], v[138:139], v[170:171]
	v_pk_fma_f32 v[168:169], v[84:85], v[210:211], v[168:169]
	v_pk_fma_f32 v[170:171], v[86:87], v[212:213], v[170:171]
	v_pk_mul_f32 v[132:133], v[164:165], s[28:29] op_sel_hi:[1,0]
	v_pk_mul_f32 v[134:135], v[166:167], s[28:29] op_sel_hi:[1,0]
	v_exp_f32_e32 v132, v132
	v_exp_f32_e32 v133, v133
	v_exp_f32_e32 v134, v134
	v_exp_f32_e32 v135, v135
	v_pk_add_f32 v[132:133], v[132:133], s[28:29] op_sel:[0,1] op_sel_hi:[1,1]
	v_pk_add_f32 v[134:135], v[134:135], s[28:29] op_sel:[0,1] op_sel_hi:[1,1]
	v_rcp_f32_e32 v132, v132
	v_rcp_f32_e32 v133, v133
	v_rcp_f32_e32 v134, v134
	v_rcp_f32_e32 v135, v135
	v_pk_mul_f32 v[164:165], v[164:165], v[132:133]
	v_pk_mul_f32 v[166:167], v[166:167], v[134:135]
	v_pk_mul_f32 v[164:165], v[164:165], v[168:169]
	v_pk_mul_f32 v[166:167], v[166:167], v[170:171]
	v_cvt_pk_bf16_f32 v164, v164, v165
	v_cvt_pk_bf16_f32 v165, v166, v167
	v_add_u32_e32 v181, 0x58000, v155
	global_store_dwordx2 v181, v[164:165], s[0:1]
	v_mov_b32_dpp v222, v88 row_shr:1 row_mask:0xf bank_mask:0xf
	v_mov_b32_dpp v223, v89 row_shr:1 row_mask:0xf bank_mask:0xf
	v_mov_b32_dpp v224, v90 row_shr:1 row_mask:0xf bank_mask:0xf
	v_mov_b32_dpp v225, v91 row_shr:1 row_mask:0xf bank_mask:0xf
	v_mov_b32_dpp v230, v88 row_shr:2 row_mask:0xf bank_mask:0xf
	v_mov_b32_dpp v231, v89 row_shr:2 row_mask:0xf bank_mask:0xf
	v_mov_b32_dpp v232, v90 row_shr:2 row_mask:0xf bank_mask:0xf
	v_mov_b32_dpp v233, v91 row_shr:2 row_mask:0xf bank_mask:0xf
	v_mov_b32_dpp v226, v28 row_shr:1 row_mask:0xf bank_mask:0xf
	v_mov_b32_dpp v227, v29 row_shr:1 row_mask:0xf bank_mask:0xf
	v_mov_b32_dpp v228, v30 row_shr:1 row_mask:0xf bank_mask:0xf
	v_mov_b32_dpp v229, v31 row_shr:1 row_mask:0xf bank_mask:0xf
	v_mov_b32_dpp v108, v28 row_shr:2 row_mask:0xf bank_mask:0xf
	v_mov_b32_dpp v109, v29 row_shr:2 row_mask:0xf bank_mask:0xf
	v_mov_b32_dpp v110, v30 row_shr:2 row_mask:0xf bank_mask:0xf
	v_mov_b32_dpp v111, v31 row_shr:2 row_mask:0xf bank_mask:0xf
	v_pk_fma_f32 v[164:165], v[188:189], v[230:231], v[214:215]
	v_pk_fma_f32 v[166:167], v[190:191], v[232:233], v[216:217]
	v_pk_fma_f32 v[164:165], v[196:197], v[222:223], v[164:165]
	v_pk_fma_f32 v[166:167], v[198:199], v[224:225], v[166:167]
	v_pk_fma_f32 v[164:165], v[88:89], v[204:205], v[164:165]
	v_pk_fma_f32 v[166:167], v[90:91], v[206:207], v[166:167]
	v_pk_fma_f32 v[168:169], v[192:193], v[108:109], v[218:219]
	v_pk_fma_f32 v[170:171], v[194:195], v[110:111], v[220:221]
	v_pk_fma_f32 v[168:169], v[200:201], v[226:227], v[168:169]
	v_pk_fma_f32 v[170:171], v[202:203], v[228:229], v[170:171]
	v_pk_fma_f32 v[168:169], v[28:29], v[210:211], v[168:169]
	v_pk_fma_f32 v[170:171], v[30:31], v[212:213], v[170:171]
	v_pk_mul_f32 v[222:223], v[164:165], s[28:29] op_sel_hi:[1,0]
	v_pk_mul_f32 v[224:225], v[166:167], s[28:29] op_sel_hi:[1,0]
	v_exp_f32_e32 v222, v222
	v_exp_f32_e32 v223, v223
	v_exp_f32_e32 v224, v224
	v_exp_f32_e32 v225, v225
	v_pk_add_f32 v[222:223], v[222:223], s[28:29] op_sel:[0,1] op_sel_hi:[1,1]
	v_pk_add_f32 v[224:225], v[224:225], s[28:29] op_sel:[0,1] op_sel_hi:[1,1]
	v_rcp_f32_e32 v222, v222
	v_rcp_f32_e32 v223, v223
	v_rcp_f32_e32 v224, v224
	v_rcp_f32_e32 v225, v225
	v_pk_mul_f32 v[164:165], v[164:165], v[222:223]
	v_pk_mul_f32 v[166:167], v[166:167], v[224:225]
	v_pk_mul_f32 v[164:165], v[164:165], v[168:169]
	v_pk_mul_f32 v[166:167], v[166:167], v[170:171]
; #define LAS __attribute__((address_space(3)))
; __device__ __forceinline__ unsigned cvt_pk_bf16(float lo, float hi) { unsigned r; asm volatile("v_cvt_pk_bf16_f32 %0, %1, %2" : "=v"(r) : "v"(lo), "v"(hi)); return r; }
; __device__ __forceinline__ float sigmoidf_(float x) { return __builtin_amdgcn_rcpf(1.0f + __expf(-x)); }
; __device__ __forceinline__ float dpp_ror1(float v) { return __int_as_float(__builtin_amdgcn_update_dpp(0, __float_as_int(v), 0x121, 0xf, 0xf, false)); }
;     __device__ __forceinline__ void conv_rows(const f32x4 curg, const f32x4 curv, f32x4 (&q1)[2], f32x4 (&q2)[2], const LAS float* cp, bf16_t* dst, const bool upd) const {
;         f32x4 uc[2];
; #pragma unroll
;         for (int bj = 0; bj < 2; ++bj) {
;             const f32x4 c0 = *(const LAS f32x4*)(cp + bj * 32), c1 = *(const LAS f32x4*)(cp + bj * 32 + 64), c2 = *(const LAS f32x4*)(cp + bj * 32 + 128), bb = *(const LAS f32x4*)(cp + bj * 32 + 192);
;             const f32x4 cur = bj ? curv : curg;
; #pragma unroll
;             for (int e = 0; e < 4; ++e) {
;                 const float p1 = dpp_shr1(q1[bj][e], cur[e]), p2 = dpp_shr2(q2[bj][e], cur[e]);
;                 uc[bj][e] = bb[e] + c0[e] * p2 + c1[e] * p1 + c2[e] * cur[e];
;                 if (upd) { q1[bj][e] = dpp_ror1(cur[e]); q2[bj][e] = dpp_ror2(cur[e]); }
;             }
;         }
;         u32x2 w;
;         { const float a0 = uc[0][0] * sigmoidf_(uc[0][0]) * uc[1][0], a1 = uc[0][1] * sigmoidf_(uc[0][1]) * uc[1][1];
;           const float a2 = uc[0][2] * sigmoidf_(uc[0][2]) * uc[1][2], a3 = uc[0][3] * sigmoidf_(uc[0][3]) * uc[1][3];
;           w.x = cvt_pk_bf16(a0, a1); w.y = cvt_pk_bf16(a2, a3); }
;         *(u32x2*)dst = w;
;     __device__ __forceinline__ void operator()(f32x4 (&acc)[2][2][4][2], const Unit& u, int wr, int wc, int fr, int fq) const {
;     ...
;                 f32x4 q1[2], q2[2];
; #pragma unroll
;                 for (int bj = 0; bj < 2; ++bj)
; #pragma unroll
;                     for (int e = 0; e < 4; ++e) { q1[bj][e] = dpp_ror1(acc[ai][bj][0][n][e]); q2[bj][e] = dpp_ror2(acc[ai][bj][0][n][e]); }
; #pragma unroll
;                 for (int m = 1; m < 4; ++m) conv_rows(acc[ai][0][m][n], acc[ai][1][m][n], q1, q2, cp, act + (size_t)(rowt + ai * HALF + m * 16) * FF + jcol, m < 3);
	v_cvt_pk_bf16_f32 v164, v164, v165
	v_cvt_pk_bf16_f32 v165, v166, v167
	v_add_u32_e32 v181, 0x84000, v155
	global_store_dwordx2 v181, v[164:165], s[0:1]
	v_mov_b32_dpp v222, v76 row_ror:1 row_mask:0xf bank_mask:0xf
	v_mov_b32_dpp v223, v77 row_ror:1 row_mask:0xf bank_mask:0xf
	v_mov_b32_dpp v224, v78 row_ror:1 row_mask:0xf bank_mask:0xf
	v_mov_b32_dpp v225, v79 row_ror:1 row_mask:0xf bank_mask:0xf
	v_mov_b32_dpp v230, v76 row_ror:2 row_mask:0xf bank_mask:0xf
	v_mov_b32_dpp v231, v77 row_ror:2 row_mask:0xf bank_mask:0xf
	v_mov_b32_dpp v232, v78 row_ror:2 row_mask:0xf bank_mask:0xf
	v_mov_b32_dpp v233, v79 row_ror:2 row_mask:0xf bank_mask:0xf
	v_mov_b32_dpp v226, v60 row_ror:1 row_mask:0xf bank_mask:0xf
	v_mov_b32_dpp v227, v61 row_ror:1 row_mask:0xf bank_mask:0xf
	v_mov_b32_dpp v228, v62 row_ror:1 row_mask:0xf bank_mask:0xf
	v_mov_b32_dpp v229, v63 row_ror:1 row_mask:0xf bank_mask:0xf
	v_mov_b32_dpp v108, v60 row_ror:2 row_mask:0xf bank_mask:0xf
	v_mov_b32_dpp v109, v61 row_ror:2 row_mask:0xf bank_mask:0xf
	v_mov_b32_dpp v110, v62 row_ror:2 row_mask:0xf bank_mask:0xf
	v_mov_b32_dpp v111, v63 row_ror:2 row_mask:0xf bank_mask:0xf
	v_mov_b32_dpp v222, v68 row_shr:1 row_mask:0xf bank_mask:0xf
	v_mov_b32_dpp v223, v69 row_shr:1 row_mask:0xf bank_mask:0xf
	v_mov_b32_dpp v224, v70 row_shr:1 row_mask:0xf bank_mask:0xf
	v_mov_b32_dpp v225, v71 row_shr:1 row_mask:0xf bank_mask:0xf
	v_mov_b32_dpp v230, v68 row_shr:2 row_mask:0xf bank_mask:0xf
	v_mov_b32_dpp v231, v69 row_shr:2 row_mask:0xf bank_mask:0xf
	v_mov_b32_dpp v232, v70 row_shr:2 row_mask:0xf bank_mask:0xf
	v_mov_b32_dpp v233, v71 row_shr:2 row_mask:0xf bank_mask:0xf
	v_mov_b32_dpp v226, v44 row_shr:1 row_mask:0xf bank_mask:0xf
	v_mov_b32_dpp v227, v45 row_shr:1 row_mask:0xf bank_mask:0xf
	v_mov_b32_dpp v228, v46 row_shr:1 row_mask:0xf bank_mask:0xf
	v_mov_b32_dpp v229, v47 row_shr:1 row_mask:0xf bank_mask:0xf
	v_mov_b32_dpp v108, v44 row_shr:2 row_mask:0xf bank_mask:0xf
	v_mov_b32_dpp v109, v45 row_shr:2 row_mask:0xf bank_mask:0xf
	v_mov_b32_dpp v110, v46 row_shr:2 row_mask:0xf bank_mask:0xf
	v_mov_b32_dpp v111, v47 row_shr:2 row_mask:0xf bank_mask:0xf
	v_mov_b32_dpp v132, v68 row_ror:1 row_mask:0xf bank_mask:0xf
	v_mov_b32_dpp v133, v69 row_ror:1 row_mask:0xf bank_mask:0xf
	v_mov_b32_dpp v134, v70 row_ror:1 row_mask:0xf bank_mask:0xf
	v_mov_b32_dpp v135, v71 row_ror:1 row_mask:0xf bank_mask:0xf
	v_mov_b32_dpp v156, v68 row_ror:2 row_mask:0xf bank_mask:0xf
	v_mov_b32_dpp v157, v69 row_ror:2 row_mask:0xf bank_mask:0xf
	v_mov_b32_dpp v158, v70 row_ror:2 row_mask:0xf bank_mask:0xf
	v_mov_b32_dpp v159, v71 row_ror:2 row_mask:0xf bank_mask:0xf
	v_mov_b32_dpp v136, v44 row_ror:1 row_mask:0xf bank_mask:0xf
	v_mov_b32_dpp v137, v45 row_ror:1 row_mask:0xf bank_mask:0xf
	v_mov_b32_dpp v138, v46 row_ror:1 row_mask:0xf bank_mask:0xf
	v_mov_b32_dpp v139, v47 row_ror:1 row_mask:0xf bank_mask:0xf
	v_mov_b32_dpp v160, v44 row_ror:2 row_mask:0xf bank_mask:0xf
	v_mov_b32_dpp v161, v45 row_ror:2 row_mask:0xf bank_mask:0xf
	v_mov_b32_dpp v162, v46 row_ror:2 row_mask:0xf bank_mask:0xf
	v_mov_b32_dpp v163, v47 row_ror:2 row_mask:0xf bank_mask:0xf
	v_pk_fma_f32 v[164:165], v[188:189], v[230:231], v[214:215]
	v_pk_fma_f32 v[166:167], v[190:191], v[232:233], v[216:217]
	v_pk_fma_f32 v[164:165], v[196:197], v[222:223], v[164:165]
	v_pk_fma_f32 v[166:167], v[198:199], v[224:225], v[166:167]
	v_pk_fma_f32 v[164:165], v[68:69], v[204:205], v[164:165]
	v_pk_fma_f32 v[166:167], v[70:71], v[206:207], v[166:167]
	v_pk_fma_f32 v[168:169], v[192:193], v[108:109], v[218:219]
	v_pk_fma_f32 v[170:171], v[194:195], v[110:111], v[220:221]
	v_pk_fma_f32 v[168:169], v[200:201], v[226:227], v[168:169]
	v_pk_fma_f32 v[170:171], v[202:203], v[228:229], v[170:171]
	v_pk_fma_f32 v[168:169], v[44:45], v[210:211], v[168:169]
	v_pk_fma_f32 v[170:171], v[46:47], v[212:213], v[170:171]
	v_pk_mul_f32 v[222:223], v[164:165], s[28:29] op_sel_hi:[1,0]
	v_pk_mul_f32 v[224:225], v[166:167], s[28:29] op_sel_hi:[1,0]
	v_exp_f32_e32 v222, v222
	v_exp_f32_e32 v223, v223
	v_exp_f32_e32 v224, v224
	v_exp_f32_e32 v225, v225
	v_pk_add_f32 v[222:223], v[222:223], s[28:29] op_sel:[0,1] op_sel_hi:[1,1]
	v_pk_add_f32 v[224:225], v[224:225], s[28:29] op_sel:[0,1] op_sel_hi:[1,1]
	v_rcp_f32_e32 v222, v222
	v_rcp_f32_e32 v223, v223
	v_rcp_f32_e32 v224, v224
	v_rcp_f32_e32 v225, v225
	v_pk_mul_f32 v[164:165], v[164:165], v[222:223]
	v_pk_mul_f32 v[166:167], v[166:167], v[224:225]
	v_pk_mul_f32 v[164:165], v[164:165], v[168:169]
	v_pk_mul_f32 v[166:167], v[166:167], v[170:171]
	v_cvt_pk_bf16_f32 v164, v164, v165
	v_cvt_pk_bf16_f32 v165, v166, v167
	v_add_u32_e32 v181, 0x18c000, v155
	global_store_dwordx2 v181, v[164:165], s[0:1]
	v_mov_b32_dpp v132, v52 row_shr:1 row_mask:0xf bank_mask:0xf
	v_mov_b32_dpp v133, v53 row_shr:1 row_mask:0xf bank_mask:0xf
	v_mov_b32_dpp v134, v54 row_shr:1 row_mask:0xf bank_mask:0xf
	v_mov_b32_dpp v135, v55 row_shr:1 row_mask:0xf bank_mask:0xf
	v_mov_b32_dpp v156, v52 row_shr:2 row_mask:0xf bank_mask:0xf
	v_mov_b32_dpp v157, v53 row_shr:2 row_mask:0xf bank_mask:0xf
	v_mov_b32_dpp v158, v54 row_shr:2 row_mask:0xf bank_mask:0xf
	v_mov_b32_dpp v159, v55 row_shr:2 row_mask:0xf bank_mask:0xf
	v_mov_b32_dpp v136, v36 row_shr:1 row_mask:0xf bank_mask:0xf
	v_mov_b32_dpp v137, v37 row_shr:1 row_mask:0xf bank_mask:0xf
	v_mov_b32_dpp v138, v38 row_shr:1 row_mask:0xf bank_mask:0xf
	v_mov_b32_dpp v139, v39 row_shr:1 row_mask:0xf bank_mask:0xf
	v_mov_b32_dpp v160, v36 row_shr:2 row_mask:0xf bank_mask:0xf
	v_mov_b32_dpp v161, v37 row_shr:2 row_mask:0xf bank_mask:0xf
	v_mov_b32_dpp v162, v38 row_shr:2 row_mask:0xf bank_mask:0xf
; #define LAS __attribute__((address_space(3)))
; __device__ __forceinline__ unsigned cvt_pk_bf16(float lo, float hi) { unsigned r; asm volatile("v_cvt_pk_bf16_f32 %0, %1, %2" : "=v"(r) : "v"(lo), "v"(hi)); return r; }
; __device__ __forceinline__ float sigmoidf_(float x) { return __builtin_amdgcn_rcpf(1.0f + __expf(-x)); }
;     __device__ __forceinline__ void conv_rows(const f32x4 curg, const f32x4 curv, f32x4 (&q1)[2], f32x4 (&q2)[2], const LAS float* cp, bf16_t* dst, const bool upd) const {
;         f32x4 uc[2];
; #pragma unroll
;         for (int bj = 0; bj < 2; ++bj) {
;             const f32x4 c0 = *(const LAS f32x4*)(cp + bj * 32), c1 = *(const LAS f32x4*)(cp + bj * 32 + 64), c2 = *(const LAS f32x4*)(cp + bj * 32 + 128), bb = *(const LAS f32x4*)(cp + bj * 32 + 192);
;             const f32x4 cur = bj ? curv : curg;
; #pragma unroll
;             for (int e = 0; e < 4; ++e) {
;                 const float p1 = dpp_shr1(q1[bj][e], cur[e]), p2 = dpp_shr2(q2[bj][e], cur[e]);
;                 uc[bj][e] = bb[e] + c0[e] * p2 + c1[e] * p1 + c2[e] * cur[e];
;                 if (upd) { q1[bj][e] = dpp_ror1(cur[e]); q2[bj][e] = dpp_ror2(cur[e]); }
;             }
;         }
;         u32x2 w;
;         { const float a0 = uc[0][0] * sigmoidf_(uc[0][0]) * uc[1][0], a1 = uc[0][1] * sigmoidf_(uc[0][1]) * uc[1][1];
;           const float a2 = uc[0][2] * sigmoidf_(uc[0][2]) * uc[1][2], a3 = uc[0][3] * sigmoidf_(uc[0][3]) * uc[1][3];
;           w.x = cvt_pk_bf16(a0, a1); w.y = cvt_pk_bf16(a2, a3); }
;         *(u32x2*)dst = w;
;     __device__ __forceinline__ void operator()(f32x4 (&acc)[2][2][4][2], const Unit& u, int wr, int wc, int fr, int fq) const {
;     ...
;         for (int n = 0; n < 2; ++n) {
;             const int jcol = u.pn * HALF + cl0 + n * 16; const LAS float* cp = myc + 16 * n + 4 * fq;
; #pragma unroll
;             for (int ai = 0; ai < 2; ++ai) {
;                 f32x4 q1[2], q2[2];
; #pragma unroll
;                 for (int bj = 0; bj < 2; ++bj)
; #pragma unroll
;                     for (int e = 0; e < 4; ++e) { q1[bj][e] = dpp_ror1(acc[ai][bj][0][n][e]); q2[bj][e] = dpp_ror2(acc[ai][bj][0][n][e]); }
; #pragma unroll
;                 for (int m = 1; m < 4; ++m) conv_rows(acc[ai][0][m][n], acc[ai][1][m][n], q1, q2, cp, act + (size_t)(rowt + ai * HALF + m * 16) * FF + jcol, m < 3);
	v_mov_b32_dpp v163, v39 row_shr:2 row_mask:0xf bank_mask:0xf
	v_mov_b32_dpp v222, v52 row_ror:1 row_mask:0xf bank_mask:0xf
	v_mov_b32_dpp v223, v53 row_ror:1 row_mask:0xf bank_mask:0xf
	v_mov_b32_dpp v224, v54 row_ror:1 row_mask:0xf bank_mask:0xf
	v_mov_b32_dpp v225, v55 row_ror:1 row_mask:0xf bank_mask:0xf
	v_mov_b32_dpp v230, v52 row_ror:2 row_mask:0xf bank_mask:0xf
	v_mov_b32_dpp v231, v53 row_ror:2 row_mask:0xf bank_mask:0xf
	v_mov_b32_dpp v232, v54 row_ror:2 row_mask:0xf bank_mask:0xf
	v_mov_b32_dpp v233, v55 row_ror:2 row_mask:0xf bank_mask:0xf
	v_mov_b32_dpp v226, v36 row_ror:1 row_mask:0xf bank_mask:0xf
	v_mov_b32_dpp v227, v37 row_ror:1 row_mask:0xf bank_mask:0xf
	v_mov_b32_dpp v228, v38 row_ror:1 row_mask:0xf bank_mask:0xf
	v_mov_b32_dpp v229, v39 row_ror:1 row_mask:0xf bank_mask:0xf
	v_mov_b32_dpp v108, v36 row_ror:2 row_mask:0xf bank_mask:0xf
	v_mov_b32_dpp v109, v37 row_ror:2 row_mask:0xf bank_mask:0xf
	v_mov_b32_dpp v110, v38 row_ror:2 row_mask:0xf bank_mask:0xf
	v_mov_b32_dpp v111, v39 row_ror:2 row_mask:0xf bank_mask:0xf
	v_pk_fma_f32 v[164:165], v[188:189], v[156:157], v[214:215]
	v_pk_fma_f32 v[166:167], v[190:191], v[158:159], v[216:217]
	v_pk_fma_f32 v[164:165], v[196:197], v[132:133], v[164:165]
	v_pk_fma_f32 v[166:167], v[198:199], v[134:135], v[166:167]
	v_pk_fma_f32 v[164:165], v[52:53], v[204:205], v[164:165]
	v_pk_fma_f32 v[166:167], v[54:55], v[206:207], v[166:167]
	v_pk_fma_f32 v[168:169], v[192:193], v[160:161], v[218:219]
	v_pk_fma_f32 v[170:171], v[194:195], v[162:163], v[220:221]
	v_pk_fma_f32 v[168:169], v[200:201], v[136:137], v[168:169]
	v_pk_fma_f32 v[170:171], v[202:203], v[138:139], v[170:171]
	v_pk_fma_f32 v[168:169], v[36:37], v[210:211], v[168:169]
	v_pk_fma_f32 v[170:171], v[38:39], v[212:213], v[170:171]
	v_pk_mul_f32 v[132:133], v[164:165], s[28:29] op_sel_hi:[1,0]
	v_pk_mul_f32 v[134:135], v[166:167], s[28:29] op_sel_hi:[1,0]
	v_exp_f32_e32 v132, v132
	v_exp_f32_e32 v133, v133
	v_exp_f32_e32 v134, v134
	v_exp_f32_e32 v135, v135
	v_pk_add_f32 v[132:133], v[132:133], s[28:29] op_sel:[0,1] op_sel_hi:[1,1]
	v_pk_add_f32 v[134:135], v[134:135], s[28:29] op_sel:[0,1] op_sel_hi:[1,1]
	v_rcp_f32_e32 v132, v132
	v_rcp_f32_e32 v133, v133
	v_rcp_f32_e32 v134, v134
	v_rcp_f32_e32 v135, v135
	v_pk_mul_f32 v[164:165], v[164:165], v[132:133]
	v_pk_mul_f32 v[166:167], v[166:167], v[134:135]
	v_pk_mul_f32 v[164:165], v[164:165], v[168:169]
	v_pk_mul_f32 v[166:167], v[166:167], v[170:171]
	v_cvt_pk_bf16_f32 v164, v164, v165
	v_cvt_pk_bf16_f32 v165, v166, v167
	v_add_u32_e32 v181, 0x1b8000, v155
	global_store_dwordx2 v181, v[164:165], s[0:1]
	v_mov_b32_dpp v222, v16 row_shr:1 row_mask:0xf bank_mask:0xf
	v_mov_b32_dpp v223, v17 row_shr:1 row_mask:0xf bank_mask:0xf
	v_mov_b32_dpp v224, v18 row_shr:1 row_mask:0xf bank_mask:0xf
	v_mov_b32_dpp v225, v19 row_shr:1 row_mask:0xf bank_mask:0xf
	v_mov_b32_dpp v230, v16 row_shr:2 row_mask:0xf bank_mask:0xf
	v_mov_b32_dpp v231, v17 row_shr:2 row_mask:0xf bank_mask:0xf
	v_mov_b32_dpp v232, v18 row_shr:2 row_mask:0xf bank_mask:0xf
	v_mov_b32_dpp v233, v19 row_shr:2 row_mask:0xf bank_mask:0xf
	v_mov_b32_dpp v226, v4 row_shr:1 row_mask:0xf bank_mask:0xf
	v_mov_b32_dpp v227, v5 row_shr:1 row_mask:0xf bank_mask:0xf
	v_mov_b32_dpp v228, v6 row_shr:1 row_mask:0xf bank_mask:0xf
	v_mov_b32_dpp v229, v7 row_shr:1 row_mask:0xf bank_mask:0xf
	v_mov_b32_dpp v108, v4 row_shr:2 row_mask:0xf bank_mask:0xf
	v_mov_b32_dpp v109, v5 row_shr:2 row_mask:0xf bank_mask:0xf
	v_mov_b32_dpp v110, v6 row_shr:2 row_mask:0xf bank_mask:0xf
	v_mov_b32_dpp v111, v7 row_shr:2 row_mask:0xf bank_mask:0xf
	v_pk_fma_f32 v[164:165], v[188:189], v[230:231], v[214:215]
	v_pk_fma_f32 v[166:167], v[190:191], v[232:233], v[216:217]
	v_pk_fma_f32 v[164:165], v[196:197], v[222:223], v[164:165]
	v_pk_fma_f32 v[166:167], v[198:199], v[224:225], v[166:167]
	v_pk_fma_f32 v[164:165], v[16:17], v[204:205], v[164:165]
	v_pk_fma_f32 v[166:167], v[18:19], v[206:207], v[166:167]
	v_pk_fma_f32 v[168:169], v[192:193], v[108:109], v[218:219]
	v_pk_fma_f32 v[170:171], v[194:195], v[110:111], v[220:221]
	v_pk_fma_f32 v[168:169], v[200:201], v[226:227], v[168:169]
	v_pk_fma_f32 v[170:171], v[202:203], v[228:229], v[170:171]
	v_pk_fma_f32 v[168:169], v[4:5], v[210:211], v[168:169]
	v_pk_fma_f32 v[170:171], v[6:7], v[212:213], v[170:171]
	v_pk_mul_f32 v[222:223], v[164:165], s[28:29] op_sel_hi:[1,0]
	v_pk_mul_f32 v[224:225], v[166:167], s[28:29] op_sel_hi:[1,0]
	v_exp_f32_e32 v222, v222
	v_exp_f32_e32 v223, v223
	v_exp_f32_e32 v224, v224
	v_exp_f32_e32 v225, v225
	v_pk_add_f32 v[222:223], v[222:223], s[28:29] op_sel:[0,1] op_sel_hi:[1,1]
	v_pk_add_f32 v[224:225], v[224:225], s[28:29] op_sel:[0,1] op_sel_hi:[1,1]
	v_rcp_f32_e32 v222, v222
	v_rcp_f32_e32 v223, v223
	v_rcp_f32_e32 v224, v224
	v_rcp_f32_e32 v225, v225
	v_pk_mul_f32 v[164:165], v[164:165], v[222:223]
	v_pk_mul_f32 v[166:167], v[166:167], v[224:225]
	v_pk_mul_f32 v[164:165], v[164:165], v[168:169]
	v_pk_mul_f32 v[166:167], v[166:167], v[170:171]
	v_cvt_pk_bf16_f32 v164, v164, v165
	v_cvt_pk_bf16_f32 v165, v166, v167
	v_add_u32_e32 v181, 0x1e4000, v155
	global_store_dwordx2 v181, v[164:165], s[0:1]
	ds_read_b128 v[188:191], v153 offset:64
	ds_read_b128 v[192:195], v153 offset:192
	ds_read_b128 v[196:199], v153 offset:320
	ds_read_b128 v[200:203], v153 offset:448
	ds_read_b128 v[204:207], v153 offset:576
	ds_read_b128 v[210:213], v153 offset:704
	ds_read_b128 v[214:217], v153 offset:832
	ds_read_b128 v[218:221], v153 offset:960
	v_mov_b32_dpp v222, v124 row_ror:1 row_mask:0xf bank_mask:0xf
	v_mov_b32_dpp v223, v125 row_ror:1 row_mask:0xf bank_mask:0xf
	v_mov_b32_dpp v224, v126 row_ror:1 row_mask:0xf bank_mask:0xf
	v_mov_b32_dpp v225, v127 row_ror:1 row_mask:0xf bank_mask:0xf
	v_mov_b32_dpp v230, v124 row_ror:2 row_mask:0xf bank_mask:0xf
	v_mov_b32_dpp v231, v125 row_ror:2 row_mask:0xf bank_mask:0xf
	v_mov_b32_dpp v232, v126 row_ror:2 row_mask:0xf bank_mask:0xf
	v_mov_b32_dpp v233, v127 row_ror:2 row_mask:0xf bank_mask:0xf
	v_mov_b32_dpp v226, v120 row_ror:1 row_mask:0xf bank_mask:0xf
	v_mov_b32_dpp v227, v121 row_ror:1 row_mask:0xf bank_mask:0xf
	v_mov_b32_dpp v228, v122 row_ror:1 row_mask:0xf bank_mask:0xf
	v_mov_b32_dpp v229, v123 row_ror:1 row_mask:0xf bank_mask:0xf
	v_mov_b32_dpp v108, v120 row_ror:2 row_mask:0xf bank_mask:0xf
	v_mov_b32_dpp v109, v121 row_ror:2 row_mask:0xf bank_mask:0xf
	v_mov_b32_dpp v110, v122 row_ror:2 row_mask:0xf bank_mask:0xf
	v_mov_b32_dpp v111, v123 row_ror:2 row_mask:0xf bank_mask:0xf
	s_waitcnt lgkmcnt(0)
; #define LAS __attribute__((address_space(3)))
; __device__ __forceinline__ unsigned cvt_pk_bf16(float lo, float hi) { unsigned r; asm volatile("v_cvt_pk_bf16_f32 %0, %1, %2" : "=v"(r) : "v"(lo), "v"(hi)); return r; }
; __device__ __forceinline__ float sigmoidf_(float x) { return __builtin_amdgcn_rcpf(1.0f + __expf(-x)); }
; __device__ __forceinline__ float dpp_ror1(float v) { return __int_as_float(__builtin_amdgcn_update_dpp(0, __float_as_int(v), 0x121, 0xf, 0xf, false)); }
;     __device__ __forceinline__ void conv_rows(const f32x4 curg, const f32x4 curv, f32x4 (&q1)[2], f32x4 (&q2)[2], const LAS float* cp, bf16_t* dst, const bool upd) const {
;         f32x4 uc[2];
; #pragma unroll
;         for (int bj = 0; bj < 2; ++bj) {
;             const f32x4 c0 = *(const LAS f32x4*)(cp + bj * 32), c1 = *(const LAS f32x4*)(cp + bj * 32 + 64), c2 = *(const LAS f32x4*)(cp + bj * 32 + 128), bb = *(const LAS f32x4*)(cp + bj * 32 + 192);
;             const f32x4 cur = bj ? curv : curg;
; #pragma unroll
;             for (int e = 0; e < 4; ++e) {
;                 const float p1 = dpp_shr1(q1[bj][e], cur[e]), p2 = dpp_shr2(q2[bj][e], cur[e]);
;                 uc[bj][e] = bb[e] + c0[e] * p2 + c1[e] * p1 + c2[e] * cur[e];
;                 if (upd) { q1[bj][e] = dpp_ror1(cur[e]); q2[bj][e] = dpp_ror2(cur[e]); }
;             }
;         }
;         u32x2 w;
;         { const float a0 = uc[0][0] * sigmoidf_(uc[0][0]) * uc[1][0], a1 = uc[0][1] * sigmoidf_(uc[0][1]) * uc[1][1];
;           const float a2 = uc[0][2] * sigmoidf_(uc[0][2]) * uc[1][2], a3 = uc[0][3] * sigmoidf_(uc[0][3]) * uc[1][3];
;           w.x = cvt_pk_bf16(a0, a1); w.y = cvt_pk_bf16(a2, a3); }
;         *(u32x2*)dst = w;
;     __device__ __forceinline__ void operator()(f32x4 (&acc)[2][2][4][2], const Unit& u, int wr, int wc, int fr, int fq) const {
;     ...
;                 f32x4 q1[2], q2[2];
; #pragma unroll
;                 for (int bj = 0; bj < 2; ++bj)
; #pragma unroll
;                     for (int e = 0; e < 4; ++e) { q1[bj][e] = dpp_ror1(acc[ai][bj][0][n][e]); q2[bj][e] = dpp_ror2(acc[ai][bj][0][n][e]); }
; #pragma unroll
;                 for (int m = 1; m < 4; ++m) conv_rows(acc[ai][0][m][n], acc[ai][1][m][n], q1, q2, cp, act + (size_t)(rowt + ai * HALF + m * 16) * FF + jcol, m < 3);
	v_mov_b32_dpp v222, v112 row_shr:1 row_mask:0xf bank_mask:0xf
	v_mov_b32_dpp v223, v113 row_shr:1 row_mask:0xf bank_mask:0xf
	v_mov_b32_dpp v224, v114 row_shr:1 row_mask:0xf bank_mask:0xf
	v_mov_b32_dpp v225, v115 row_shr:1 row_mask:0xf bank_mask:0xf
	v_mov_b32_dpp v230, v112 row_shr:2 row_mask:0xf bank_mask:0xf
	v_mov_b32_dpp v231, v113 row_shr:2 row_mask:0xf bank_mask:0xf
	v_mov_b32_dpp v232, v114 row_shr:2 row_mask:0xf bank_mask:0xf
	v_mov_b32_dpp v233, v115 row_shr:2 row_mask:0xf bank_mask:0xf
	v_mov_b32_dpp v226, v92 row_shr:1 row_mask:0xf bank_mask:0xf
	v_mov_b32_dpp v227, v93 row_shr:1 row_mask:0xf bank_mask:0xf
	v_mov_b32_dpp v228, v94 row_shr:1 row_mask:0xf bank_mask:0xf
	v_mov_b32_dpp v229, v95 row_shr:1 row_mask:0xf bank_mask:0xf
	v_mov_b32_dpp v108, v92 row_shr:2 row_mask:0xf bank_mask:0xf
	v_mov_b32_dpp v109, v93 row_shr:2 row_mask:0xf bank_mask:0xf
	v_mov_b32_dpp v110, v94 row_shr:2 row_mask:0xf bank_mask:0xf
	v_mov_b32_dpp v111, v95 row_shr:2 row_mask:0xf bank_mask:0xf
	v_mov_b32_dpp v132, v112 row_ror:1 row_mask:0xf bank_mask:0xf
	v_mov_b32_dpp v133, v113 row_ror:1 row_mask:0xf bank_mask:0xf
	v_mov_b32_dpp v134, v114 row_ror:1 row_mask:0xf bank_mask:0xf
	v_mov_b32_dpp v135, v115 row_ror:1 row_mask:0xf bank_mask:0xf
	v_mov_b32_dpp v156, v112 row_ror:2 row_mask:0xf bank_mask:0xf
	v_mov_b32_dpp v157, v113 row_ror:2 row_mask:0xf bank_mask:0xf
	v_mov_b32_dpp v158, v114 row_ror:2 row_mask:0xf bank_mask:0xf
	v_mov_b32_dpp v159, v115 row_ror:2 row_mask:0xf bank_mask:0xf
	v_mov_b32_dpp v136, v92 row_ror:1 row_mask:0xf bank_mask:0xf
	v_mov_b32_dpp v137, v93 row_ror:1 row_mask:0xf bank_mask:0xf
	v_mov_b32_dpp v138, v94 row_ror:1 row_mask:0xf bank_mask:0xf
	v_mov_b32_dpp v139, v95 row_ror:1 row_mask:0xf bank_mask:0xf
	v_mov_b32_dpp v160, v92 row_ror:2 row_mask:0xf bank_mask:0xf
	v_mov_b32_dpp v161, v93 row_ror:2 row_mask:0xf bank_mask:0xf
	v_mov_b32_dpp v162, v94 row_ror:2 row_mask:0xf bank_mask:0xf
	v_mov_b32_dpp v163, v95 row_ror:2 row_mask:0xf bank_mask:0xf
	v_pk_fma_f32 v[164:165], v[188:189], v[230:231], v[214:215]
	v_pk_fma_f32 v[166:167], v[190:191], v[232:233], v[216:217]
	v_pk_fma_f32 v[164:165], v[196:197], v[222:223], v[164:165]
	v_pk_fma_f32 v[166:167], v[198:199], v[224:225], v[166:167]
	v_pk_fma_f32 v[164:165], v[112:113], v[204:205], v[164:165]
	v_pk_fma_f32 v[166:167], v[114:115], v[206:207], v[166:167]
	v_pk_fma_f32 v[168:169], v[192:193], v[108:109], v[218:219]
	v_pk_fma_f32 v[170:171], v[194:195], v[110:111], v[220:221]
	v_pk_fma_f32 v[168:169], v[200:201], v[226:227], v[168:169]
	v_pk_fma_f32 v[170:171], v[202:203], v[228:229], v[170:171]
	v_pk_fma_f32 v[168:169], v[92:93], v[210:211], v[168:169]
	v_pk_fma_f32 v[170:171], v[94:95], v[212:213], v[170:171]
	v_pk_mul_f32 v[222:223], v[164:165], s[28:29] op_sel_hi:[1,0]
	v_pk_mul_f32 v[224:225], v[166:167], s[28:29] op_sel_hi:[1,0]
	v_exp_f32_e32 v222, v222
	v_exp_f32_e32 v223, v223
	v_exp_f32_e32 v224, v224
	v_exp_f32_e32 v225, v225
	v_pk_add_f32 v[222:223], v[222:223], s[28:29] op_sel:[0,1] op_sel_hi:[1,1]
	v_pk_add_f32 v[224:225], v[224:225], s[28:29] op_sel:[0,1] op_sel_hi:[1,1]
	v_rcp_f32_e32 v222, v222
	v_rcp_f32_e32 v223, v223
	v_rcp_f32_e32 v224, v224
	v_rcp_f32_e32 v225, v225
	v_pk_mul_f32 v[164:165], v[164:165], v[222:223]
	v_pk_mul_f32 v[166:167], v[166:167], v[224:225]
	v_pk_mul_f32 v[164:165], v[164:165], v[168:169]
	v_pk_mul_f32 v[166:167], v[166:167], v[170:171]
	v_cvt_pk_bf16_f32 v164, v164, v165
	v_cvt_pk_bf16_f32 v165, v166, v167
	v_add_u32_e32 v181, 0x2c000, v155
	global_store_dwordx2 v181, v[164:165], s[0:1] offset:32
	v_mov_b32_dpp v132, v96 row_shr:1 row_mask:0xf bank_mask:0xf
	v_mov_b32_dpp v133, v97 row_shr:1 row_mask:0xf bank_mask:0xf
	v_mov_b32_dpp v134, v98 row_shr:1 row_mask:0xf bank_mask:0xf
	v_mov_b32_dpp v135, v99 row_shr:1 row_mask:0xf bank_mask:0xf
	v_mov_b32_dpp v156, v96 row_shr:2 row_mask:0xf bank_mask:0xf
	v_mov_b32_dpp v157, v97 row_shr:2 row_mask:0xf bank_mask:0xf
	v_mov_b32_dpp v158, v98 row_shr:2 row_mask:0xf bank_mask:0xf
	v_mov_b32_dpp v159, v99 row_shr:2 row_mask:0xf bank_mask:0xf
	v_mov_b32_dpp v136, v80 row_shr:1 row_mask:0xf bank_mask:0xf
	v_mov_b32_dpp v137, v81 row_shr:1 row_mask:0xf bank_mask:0xf
	v_mov_b32_dpp v138, v82 row_shr:1 row_mask:0xf bank_mask:0xf
	v_mov_b32_dpp v139, v83 row_shr:1 row_mask:0xf bank_mask:0xf
	v_mov_b32_dpp v160, v80 row_shr:2 row_mask:0xf bank_mask:0xf
	v_mov_b32_dpp v161, v81 row_shr:2 row_mask:0xf bank_mask:0xf
	v_mov_b32_dpp v162, v82 row_shr:2 row_mask:0xf bank_mask:0xf
	v_mov_b32_dpp v163, v83 row_shr:2 row_mask:0xf bank_mask:0xf
	v_mov_b32_dpp v222, v96 row_ror:1 row_mask:0xf bank_mask:0xf
	v_mov_b32_dpp v223, v97 row_ror:1 row_mask:0xf bank_mask:0xf
	v_mov_b32_dpp v224, v98 row_ror:1 row_mask:0xf bank_mask:0xf
	v_mov_b32_dpp v225, v99 row_ror:1 row_mask:0xf bank_mask:0xf
	v_mov_b32_dpp v230, v96 row_ror:2 row_mask:0xf bank_mask:0xf
	v_mov_b32_dpp v231, v97 row_ror:2 row_mask:0xf bank_mask:0xf
	v_mov_b32_dpp v232, v98 row_ror:2 row_mask:0xf bank_mask:0xf
	v_mov_b32_dpp v233, v99 row_ror:2 row_mask:0xf bank_mask:0xf
	v_mov_b32_dpp v226, v80 row_ror:1 row_mask:0xf bank_mask:0xf
	v_mov_b32_dpp v227, v81 row_ror:1 row_mask:0xf bank_mask:0xf
	v_mov_b32_dpp v228, v82 row_ror:1 row_mask:0xf bank_mask:0xf
	v_mov_b32_dpp v229, v83 row_ror:1 row_mask:0xf bank_mask:0xf
	v_mov_b32_dpp v108, v80 row_ror:2 row_mask:0xf bank_mask:0xf
	v_mov_b32_dpp v109, v81 row_ror:2 row_mask:0xf bank_mask:0xf
	v_mov_b32_dpp v110, v82 row_ror:2 row_mask:0xf bank_mask:0xf
	v_mov_b32_dpp v111, v83 row_ror:2 row_mask:0xf bank_mask:0xf
	v_pk_fma_f32 v[164:165], v[188:189], v[156:157], v[214:215]
; #define LAS __attribute__((address_space(3)))
; __device__ __forceinline__ unsigned cvt_pk_bf16(float lo, float hi) { unsigned r; asm volatile("v_cvt_pk_bf16_f32 %0, %1, %2" : "=v"(r) : "v"(lo), "v"(hi)); return r; }
; __device__ __forceinline__ float sigmoidf_(float x) { return __builtin_amdgcn_rcpf(1.0f + __expf(-x)); }
; __device__ __forceinline__ float dpp_ror1(float v) { return __int_as_float(__builtin_amdgcn_update_dpp(0, __float_as_int(v), 0x121, 0xf, 0xf, false)); }
;     __device__ __forceinline__ void conv_rows(const f32x4 curg, const f32x4 curv, f32x4 (&q1)[2], f32x4 (&q2)[2], const LAS float* cp, bf16_t* dst, const bool upd) const {
;         f32x4 uc[2];
; #pragma unroll
;         for (int bj = 0; bj < 2; ++bj) {
;             const f32x4 c0 = *(const LAS f32x4*)(cp + bj * 32), c1 = *(const LAS f32x4*)(cp + bj * 32 + 64), c2 = *(const LAS f32x4*)(cp + bj * 32 + 128), bb = *(const LAS f32x4*)(cp + bj * 32 + 192);
;             const f32x4 cur = bj ? curv : curg;
; #pragma unroll
;             for (int e = 0; e < 4; ++e) {
;                 const float p1 = dpp_shr1(q1[bj][e], cur[e]), p2 = dpp_shr2(q2[bj][e], cur[e]);
;                 uc[bj][e] = bb[e] + c0[e] * p2 + c1[e] * p1 + c2[e] * cur[e];
;                 if (upd) { q1[bj][e] = dpp_ror1(cur[e]); q2[bj][e] = dpp_ror2(cur[e]); }
;             }
;         }
;         u32x2 w;
;         { const float a0 = uc[0][0] * sigmoidf_(uc[0][0]) * uc[1][0], a1 = uc[0][1] * sigmoidf_(uc[0][1]) * uc[1][1];
;           const float a2 = uc[0][2] * sigmoidf_(uc[0][2]) * uc[1][2], a3 = uc[0][3] * sigmoidf_(uc[0][3]) * uc[1][3];
;           w.x = cvt_pk_bf16(a0, a1); w.y = cvt_pk_bf16(a2, a3); }
;         *(u32x2*)dst = w;
;     __device__ __forceinline__ void operator()(f32x4 (&acc)[2][2][4][2], const Unit& u, int wr, int wc, int fr, int fq) const {
;     ...
;                 f32x4 q1[2], q2[2];
; #pragma unroll
;                 for (int bj = 0; bj < 2; ++bj)
; #pragma unroll
;                     for (int e = 0; e < 4; ++e) { q1[bj][e] = dpp_ror1(acc[ai][bj][0][n][e]); q2[bj][e] = dpp_ror2(acc[ai][bj][0][n][e]); }
; #pragma unroll
;                 for (int m = 1; m < 4; ++m) conv_rows(acc[ai][0][m][n], acc[ai][1][m][n], q1, q2, cp, act + (size_t)(rowt + ai * HALF + m * 16) * FF + jcol, m < 3);
	v_pk_fma_f32 v[166:167], v[190:191], v[158:159], v[216:217]
	v_pk_fma_f32 v[164:165], v[196:197], v[132:133], v[164:165]
	v_pk_fma_f32 v[166:167], v[198:199], v[134:135], v[166:167]
	v_pk_fma_f32 v[164:165], v[96:97], v[204:205], v[164:165]
	v_pk_fma_f32 v[166:167], v[98:99], v[206:207], v[166:167]
	v_pk_fma_f32 v[168:169], v[192:193], v[160:161], v[218:219]
	v_pk_fma_f32 v[170:171], v[194:195], v[162:163], v[220:221]
	v_pk_fma_f32 v[168:169], v[200:201], v[136:137], v[168:169]
	v_pk_fma_f32 v[170:171], v[202:203], v[138:139], v[170:171]
	v_pk_fma_f32 v[168:169], v[80:81], v[210:211], v[168:169]
	v_pk_fma_f32 v[170:171], v[82:83], v[212:213], v[170:171]
	v_pk_mul_f32 v[132:133], v[164:165], s[28:29] op_sel_hi:[1,0]
	v_pk_mul_f32 v[134:135], v[166:167], s[28:29] op_sel_hi:[1,0]
	v_exp_f32_e32 v132, v132
	v_exp_f32_e32 v133, v133
	v_exp_f32_e32 v134, v134
	v_exp_f32_e32 v135, v135
	v_pk_add_f32 v[132:133], v[132:133], s[28:29] op_sel:[0,1] op_sel_hi:[1,1]
	v_pk_add_f32 v[134:135], v[134:135], s[28:29] op_sel:[0,1] op_sel_hi:[1,1]
	v_rcp_f32_e32 v132, v132
	v_rcp_f32_e32 v133, v133
	v_rcp_f32_e32 v134, v134
	v_rcp_f32_e32 v135, v135
	v_pk_mul_f32 v[164:165], v[164:165], v[132:133]
	v_pk_mul_f32 v[166:167], v[166:167], v[134:135]
	v_pk_mul_f32 v[164:165], v[164:165], v[168:169]
	v_pk_mul_f32 v[166:167], v[166:167], v[170:171]
	v_cvt_pk_bf16_f32 v164, v164, v165
	v_cvt_pk_bf16_f32 v165, v166, v167
	v_add_u32_e32 v181, 0x58000, v155
	global_store_dwordx2 v181, v[164:165], s[0:1] offset:32
	v_mov_b32_dpp v222, v24 row_shr:1 row_mask:0xf bank_mask:0xf
	v_mov_b32_dpp v223, v25 row_shr:1 row_mask:0xf bank_mask:0xf
	v_mov_b32_dpp v224, v26 row_shr:1 row_mask:0xf bank_mask:0xf
	v_mov_b32_dpp v225, v27 row_shr:1 row_mask:0xf bank_mask:0xf
	v_mov_b32_dpp v230, v24 row_shr:2 row_mask:0xf bank_mask:0xf
	v_mov_b32_dpp v231, v25 row_shr:2 row_mask:0xf bank_mask:0xf
	v_mov_b32_dpp v232, v26 row_shr:2 row_mask:0xf bank_mask:0xf
	v_mov_b32_dpp v233, v27 row_shr:2 row_mask:0xf bank_mask:0xf
	v_mov_b32_dpp v226, v20 row_shr:1 row_mask:0xf bank_mask:0xf
	v_mov_b32_dpp v227, v21 row_shr:1 row_mask:0xf bank_mask:0xf
	v_mov_b32_dpp v228, v22 row_shr:1 row_mask:0xf bank_mask:0xf
	v_mov_b32_dpp v229, v23 row_shr:1 row_mask:0xf bank_mask:0xf
	v_mov_b32_dpp v108, v20 row_shr:2 row_mask:0xf bank_mask:0xf
	v_mov_b32_dpp v109, v21 row_shr:2 row_mask:0xf bank_mask:0xf
	v_mov_b32_dpp v110, v22 row_shr:2 row_mask:0xf bank_mask:0xf
	v_mov_b32_dpp v111, v23 row_shr:2 row_mask:0xf bank_mask:0xf
	v_pk_fma_f32 v[164:165], v[188:189], v[230:231], v[214:215]
	v_pk_fma_f32 v[166:167], v[190:191], v[232:233], v[216:217]
	v_pk_fma_f32 v[164:165], v[196:197], v[222:223], v[164:165]
	v_pk_fma_f32 v[166:167], v[198:199], v[224:225], v[166:167]
	v_pk_fma_f32 v[164:165], v[24:25], v[204:205], v[164:165]
	v_pk_fma_f32 v[166:167], v[26:27], v[206:207], v[166:167]
	v_pk_fma_f32 v[168:169], v[192:193], v[108:109], v[218:219]
	v_pk_fma_f32 v[170:171], v[194:195], v[110:111], v[220:221]
	v_pk_fma_f32 v[168:169], v[200:201], v[226:227], v[168:169]
	v_pk_fma_f32 v[170:171], v[202:203], v[228:229], v[170:171]
	v_pk_fma_f32 v[168:169], v[20:21], v[210:211], v[168:169]
	v_pk_fma_f32 v[170:171], v[22:23], v[212:213], v[170:171]
	v_pk_mul_f32 v[222:223], v[164:165], s[28:29] op_sel_hi:[1,0]
	v_pk_mul_f32 v[224:225], v[166:167], s[28:29] op_sel_hi:[1,0]
	v_exp_f32_e32 v222, v222
	v_exp_f32_e32 v223, v223
	v_exp_f32_e32 v224, v224
	v_exp_f32_e32 v225, v225
	v_pk_add_f32 v[222:223], v[222:223], s[28:29] op_sel:[0,1] op_sel_hi:[1,1]
	v_pk_add_f32 v[224:225], v[224:225], s[28:29] op_sel:[0,1] op_sel_hi:[1,1]
	v_rcp_f32_e32 v222, v222
	v_rcp_f32_e32 v223, v223
	v_rcp_f32_e32 v224, v224
	v_rcp_f32_e32 v225, v225
	v_pk_mul_f32 v[164:165], v[164:165], v[222:223]
	v_pk_mul_f32 v[166:167], v[166:167], v[224:225]
	v_pk_mul_f32 v[164:165], v[164:165], v[168:169]
	v_pk_mul_f32 v[166:167], v[166:167], v[170:171]
	v_cvt_pk_bf16_f32 v164, v164, v165
	v_cvt_pk_bf16_f32 v165, v166, v167
	v_add_u32_e32 v181, 0x84000, v155
	global_store_dwordx2 v181, v[164:165], s[0:1] offset:32
	v_mov_b32_dpp v222, v72 row_ror:1 row_mask:0xf bank_mask:0xf
	v_mov_b32_dpp v223, v73 row_ror:1 row_mask:0xf bank_mask:0xf
	v_mov_b32_dpp v224, v74 row_ror:1 row_mask:0xf bank_mask:0xf
	v_mov_b32_dpp v225, v75 row_ror:1 row_mask:0xf bank_mask:0xf
	v_mov_b32_dpp v230, v72 row_ror:2 row_mask:0xf bank_mask:0xf
	v_mov_b32_dpp v231, v73 row_ror:2 row_mask:0xf bank_mask:0xf
	v_mov_b32_dpp v232, v74 row_ror:2 row_mask:0xf bank_mask:0xf
	v_mov_b32_dpp v233, v75 row_ror:2 row_mask:0xf bank_mask:0xf
	v_mov_b32_dpp v226, v56 row_ror:1 row_mask:0xf bank_mask:0xf
	v_mov_b32_dpp v227, v57 row_ror:1 row_mask:0xf bank_mask:0xf
	v_mov_b32_dpp v228, v58 row_ror:1 row_mask:0xf bank_mask:0xf
	v_mov_b32_dpp v229, v59 row_ror:1 row_mask:0xf bank_mask:0xf
	v_mov_b32_dpp v108, v56 row_ror:2 row_mask:0xf bank_mask:0xf
	v_mov_b32_dpp v109, v57 row_ror:2 row_mask:0xf bank_mask:0xf
	v_mov_b32_dpp v110, v58 row_ror:2 row_mask:0xf bank_mask:0xf
	v_mov_b32_dpp v111, v59 row_ror:2 row_mask:0xf bank_mask:0xf
	v_mov_b32_dpp v222, v64 row_shr:1 row_mask:0xf bank_mask:0xf
	v_mov_b32_dpp v223, v65 row_shr:1 row_mask:0xf bank_mask:0xf
	v_mov_b32_dpp v224, v66 row_shr:1 row_mask:0xf bank_mask:0xf
	v_mov_b32_dpp v225, v67 row_shr:1 row_mask:0xf bank_mask:0xf
	v_mov_b32_dpp v230, v64 row_shr:2 row_mask:0xf bank_mask:0xf
	v_mov_b32_dpp v231, v65 row_shr:2 row_mask:0xf bank_mask:0xf
	v_mov_b32_dpp v232, v66 row_shr:2 row_mask:0xf bank_mask:0xf
	v_mov_b32_dpp v233, v67 row_shr:2 row_mask:0xf bank_mask:0xf
	v_mov_b32_dpp v226, v40 row_shr:1 row_mask:0xf bank_mask:0xf
; #define LAS __attribute__((address_space(3)))
; __device__ __forceinline__ unsigned cvt_pk_bf16(float lo, float hi) { unsigned r; asm volatile("v_cvt_pk_bf16_f32 %0, %1, %2" : "=v"(r) : "v"(lo), "v"(hi)); return r; }
; __device__ __forceinline__ float sigmoidf_(float x) { return __builtin_amdgcn_rcpf(1.0f + __expf(-x)); }
; __device__ __forceinline__ float dpp_ror1(float v) { return __int_as_float(__builtin_amdgcn_update_dpp(0, __float_as_int(v), 0x121, 0xf, 0xf, false)); }
;     __device__ __forceinline__ void conv_rows(const f32x4 curg, const f32x4 curv, f32x4 (&q1)[2], f32x4 (&q2)[2], const LAS float* cp, bf16_t* dst, const bool upd) const {
;         f32x4 uc[2];
; #pragma unroll
;         for (int bj = 0; bj < 2; ++bj) {
;             const f32x4 c0 = *(const LAS f32x4*)(cp + bj * 32), c1 = *(const LAS f32x4*)(cp + bj * 32 + 64), c2 = *(const LAS f32x4*)(cp + bj * 32 + 128), bb = *(const LAS f32x4*)(cp + bj * 32 + 192);
;             const f32x4 cur = bj ? curv : curg;
; #pragma unroll
;             for (int e = 0; e < 4; ++e) {
;                 const float p1 = dpp_shr1(q1[bj][e], cur[e]), p2 = dpp_shr2(q2[bj][e], cur[e]);
;                 uc[bj][e] = bb[e] + c0[e] * p2 + c1[e] * p1 + c2[e] * cur[e];
;                 if (upd) { q1[bj][e] = dpp_ror1(cur[e]); q2[bj][e] = dpp_ror2(cur[e]); }
;             }
;         }
;         u32x2 w;
;         { const float a0 = uc[0][0] * sigmoidf_(uc[0][0]) * uc[1][0], a1 = uc[0][1] * sigmoidf_(uc[0][1]) * uc[1][1];
;           const float a2 = uc[0][2] * sigmoidf_(uc[0][2]) * uc[1][2], a3 = uc[0][3] * sigmoidf_(uc[0][3]) * uc[1][3];
;           w.x = cvt_pk_bf16(a0, a1); w.y = cvt_pk_bf16(a2, a3); }
;         *(u32x2*)dst = w;
;     __device__ __forceinline__ void operator()(f32x4 (&acc)[2][2][4][2], const Unit& u, int wr, int wc, int fr, int fq) const {
;     ...
;                 f32x4 q1[2], q2[2];
; #pragma unroll
;                 for (int bj = 0; bj < 2; ++bj)
; #pragma unroll
;                     for (int e = 0; e < 4; ++e) { q1[bj][e] = dpp_ror1(acc[ai][bj][0][n][e]); q2[bj][e] = dpp_ror2(acc[ai][bj][0][n][e]); }
; #pragma unroll
;                 for (int m = 1; m < 4; ++m) conv_rows(acc[ai][0][m][n], acc[ai][1][m][n], q1, q2, cp, act + (size_t)(rowt + ai * HALF + m * 16) * FF + jcol, m < 3);
	v_mov_b32_dpp v227, v41 row_shr:1 row_mask:0xf bank_mask:0xf
	v_mov_b32_dpp v228, v42 row_shr:1 row_mask:0xf bank_mask:0xf
	v_mov_b32_dpp v229, v43 row_shr:1 row_mask:0xf bank_mask:0xf
	v_mov_b32_dpp v108, v40 row_shr:2 row_mask:0xf bank_mask:0xf
	v_mov_b32_dpp v109, v41 row_shr:2 row_mask:0xf bank_mask:0xf
	v_mov_b32_dpp v110, v42 row_shr:2 row_mask:0xf bank_mask:0xf
	v_mov_b32_dpp v111, v43 row_shr:2 row_mask:0xf bank_mask:0xf
	v_mov_b32_dpp v132, v64 row_ror:1 row_mask:0xf bank_mask:0xf
	v_mov_b32_dpp v133, v65 row_ror:1 row_mask:0xf bank_mask:0xf
	v_mov_b32_dpp v134, v66 row_ror:1 row_mask:0xf bank_mask:0xf
	v_mov_b32_dpp v135, v67 row_ror:1 row_mask:0xf bank_mask:0xf
	v_mov_b32_dpp v156, v64 row_ror:2 row_mask:0xf bank_mask:0xf
	v_mov_b32_dpp v157, v65 row_ror:2 row_mask:0xf bank_mask:0xf
	v_mov_b32_dpp v158, v66 row_ror:2 row_mask:0xf bank_mask:0xf
	v_mov_b32_dpp v159, v67 row_ror:2 row_mask:0xf bank_mask:0xf
	v_mov_b32_dpp v136, v40 row_ror:1 row_mask:0xf bank_mask:0xf
	v_mov_b32_dpp v137, v41 row_ror:1 row_mask:0xf bank_mask:0xf
	v_mov_b32_dpp v138, v42 row_ror:1 row_mask:0xf bank_mask:0xf
	v_mov_b32_dpp v139, v43 row_ror:1 row_mask:0xf bank_mask:0xf
	v_mov_b32_dpp v160, v40 row_ror:2 row_mask:0xf bank_mask:0xf
	v_mov_b32_dpp v161, v41 row_ror:2 row_mask:0xf bank_mask:0xf
	v_mov_b32_dpp v162, v42 row_ror:2 row_mask:0xf bank_mask:0xf
	v_mov_b32_dpp v163, v43 row_ror:2 row_mask:0xf bank_mask:0xf
	v_pk_fma_f32 v[164:165], v[188:189], v[230:231], v[214:215]
	v_pk_fma_f32 v[166:167], v[190:191], v[232:233], v[216:217]
	v_pk_fma_f32 v[164:165], v[196:197], v[222:223], v[164:165]
	v_pk_fma_f32 v[166:167], v[198:199], v[224:225], v[166:167]
	v_pk_fma_f32 v[164:165], v[64:65], v[204:205], v[164:165]
	v_pk_fma_f32 v[166:167], v[66:67], v[206:207], v[166:167]
	v_pk_fma_f32 v[168:169], v[192:193], v[108:109], v[218:219]
	v_pk_fma_f32 v[170:171], v[194:195], v[110:111], v[220:221]
	v_pk_fma_f32 v[168:169], v[200:201], v[226:227], v[168:169]
	v_pk_fma_f32 v[170:171], v[202:203], v[228:229], v[170:171]
	v_pk_fma_f32 v[168:169], v[40:41], v[210:211], v[168:169]
	v_pk_fma_f32 v[170:171], v[42:43], v[212:213], v[170:171]
	v_pk_mul_f32 v[222:223], v[164:165], s[28:29] op_sel_hi:[1,0]
	v_pk_mul_f32 v[224:225], v[166:167], s[28:29] op_sel_hi:[1,0]
	v_exp_f32_e32 v222, v222
	v_exp_f32_e32 v223, v223
	v_exp_f32_e32 v224, v224
	v_exp_f32_e32 v225, v225
	v_pk_add_f32 v[222:223], v[222:223], s[28:29] op_sel:[0,1] op_sel_hi:[1,1]
	v_pk_add_f32 v[224:225], v[224:225], s[28:29] op_sel:[0,1] op_sel_hi:[1,1]
	v_rcp_f32_e32 v222, v222
	v_rcp_f32_e32 v223, v223
	v_rcp_f32_e32 v224, v224
	v_rcp_f32_e32 v225, v225
	v_pk_mul_f32 v[164:165], v[164:165], v[222:223]
	v_pk_mul_f32 v[166:167], v[166:167], v[224:225]
	v_pk_mul_f32 v[164:165], v[164:165], v[168:169]
	v_pk_mul_f32 v[166:167], v[166:167], v[170:171]
	v_cvt_pk_bf16_f32 v164, v164, v165
	v_cvt_pk_bf16_f32 v165, v166, v167
	v_add_u32_e32 v181, 0x18c000, v155
	global_store_dwordx2 v181, v[164:165], s[0:1] offset:32
	v_mov_b32_dpp v132, v48 row_shr:1 row_mask:0xf bank_mask:0xf
	v_mov_b32_dpp v133, v49 row_shr:1 row_mask:0xf bank_mask:0xf
	v_mov_b32_dpp v134, v50 row_shr:1 row_mask:0xf bank_mask:0xf
	v_mov_b32_dpp v135, v51 row_shr:1 row_mask:0xf bank_mask:0xf
	v_mov_b32_dpp v156, v48 row_shr:2 row_mask:0xf bank_mask:0xf
	v_mov_b32_dpp v157, v49 row_shr:2 row_mask:0xf bank_mask:0xf
	v_mov_b32_dpp v158, v50 row_shr:2 row_mask:0xf bank_mask:0xf
	v_mov_b32_dpp v159, v51 row_shr:2 row_mask:0xf bank_mask:0xf
	v_mov_b32_dpp v136, v32 row_shr:1 row_mask:0xf bank_mask:0xf
	v_mov_b32_dpp v137, v33 row_shr:1 row_mask:0xf bank_mask:0xf
	v_mov_b32_dpp v138, v34 row_shr:1 row_mask:0xf bank_mask:0xf
	v_mov_b32_dpp v139, v35 row_shr:1 row_mask:0xf bank_mask:0xf
	v_mov_b32_dpp v160, v32 row_shr:2 row_mask:0xf bank_mask:0xf
	v_mov_b32_dpp v161, v33 row_shr:2 row_mask:0xf bank_mask:0xf
	v_mov_b32_dpp v162, v34 row_shr:2 row_mask:0xf bank_mask:0xf
	v_mov_b32_dpp v163, v35 row_shr:2 row_mask:0xf bank_mask:0xf
	v_mov_b32_dpp v222, v48 row_ror:1 row_mask:0xf bank_mask:0xf
	v_mov_b32_dpp v223, v49 row_ror:1 row_mask:0xf bank_mask:0xf
	v_mov_b32_dpp v224, v50 row_ror:1 row_mask:0xf bank_mask:0xf
	v_mov_b32_dpp v225, v51 row_ror:1 row_mask:0xf bank_mask:0xf
	v_mov_b32_dpp v230, v48 row_ror:2 row_mask:0xf bank_mask:0xf
	v_mov_b32_dpp v231, v49 row_ror:2 row_mask:0xf bank_mask:0xf
	v_mov_b32_dpp v232, v50 row_ror:2 row_mask:0xf bank_mask:0xf
	v_mov_b32_dpp v233, v51 row_ror:2 row_mask:0xf bank_mask:0xf
	v_mov_b32_dpp v226, v32 row_ror:1 row_mask:0xf bank_mask:0xf
	v_mov_b32_dpp v227, v33 row_ror:1 row_mask:0xf bank_mask:0xf
	v_mov_b32_dpp v228, v34 row_ror:1 row_mask:0xf bank_mask:0xf
	v_mov_b32_dpp v229, v35 row_ror:1 row_mask:0xf bank_mask:0xf
	v_mov_b32_dpp v108, v32 row_ror:2 row_mask:0xf bank_mask:0xf
	v_mov_b32_dpp v109, v33 row_ror:2 row_mask:0xf bank_mask:0xf
	v_mov_b32_dpp v110, v34 row_ror:2 row_mask:0xf bank_mask:0xf
	v_mov_b32_dpp v111, v35 row_ror:2 row_mask:0xf bank_mask:0xf
	v_pk_fma_f32 v[164:165], v[188:189], v[156:157], v[214:215]
;     __device__ __forceinline__ void conv_rows(const f32x4 curg, const f32x4 curv, f32x4 (&q1)[2], f32x4 (&q2)[2], const LAS float* cp, bf16_t* dst, const bool upd) const {
;         f32x4 uc[2];
; #pragma unroll
;         for (int bj = 0; bj < 2; ++bj) {
;             const f32x4 c0 = *(const LAS f32x4*)(cp + bj * 32), c1 = *(const LAS f32x4*)(cp + bj * 32 + 64), c2 = *(const LAS f32x4*)(cp + bj * 32 + 128), bb = *(const LAS f32x4*)(cp + bj * 32 + 192);
;             const f32x4 cur = bj ? curv : curg;
; #pragma unroll
;             for (int e = 0; e < 4; ++e) {
;                 const float p1 = dpp_shr1(q1[bj][e], cur[e]), p2 = dpp_shr2(q2[bj][e], cur[e]);
;                 uc[bj][e] = bb[e] + c0[e] * p2 + c1[e] * p1 + c2[e] * cur[e];
;                 if (upd) { q1[bj][e] = dpp_ror1(cur[e]); q2[bj][e] = dpp_ror2(cur[e]); }
;             }
;         }
;         u32x2 w;
;         { const float a0 = uc[0][0] * sigmoidf_(uc[0][0]) * uc[1][0], a1 = uc[0][1] * sigmoidf_(uc[0][1]) * uc[1][1];
;           const float a2 = uc[0][2] * sigmoidf_(uc[0][2]) * uc[1][2], a3 = uc[0][3] * sigmoidf_(uc[0][3]) * uc[1][3];
;           w.x = cvt_pk_bf16(a0, a1); w.y = cvt_pk_bf16(a2, a3); }
;         *(u32x2*)dst = w;
;     __device__ __forceinline__ void operator()(f32x4 (&acc)[2][2][4][2], const Unit& u, int wr, int wc, int fr, int fq) const {
;     ...
;         asm volatile("s_waitcnt lgkmcnt(0)" ::: "memory"); PG8_BAR; PG8_BAR; asm volatile("" ::: "memory");
; #pragma unroll
;         for (int n = 0; n < 2; ++n) {
;             const int jcol = u.pn * HALF + cl0 + n * 16; const LAS float* cp = myc + 16 * n + 4 * fq;
; #pragma unroll
;             for (int ai = 0; ai < 2; ++ai) {
;                 const bool has_prev = !(ai == 0 && wr == 0);
;                 const int slot = (wr == 1) ? (ai * 2) : ((ai - 1) * 2 + 1);
;                 f32x4 q1[2], q2[2];
; #pragma unroll
;                 for (int bj = 0; bj < 2; ++bj) {
;                     f32x4 e0 = (f32x4){0.f, 0.f, 0.f, 0.f}, e1 = (f32x4){0.f, 0.f, 0.f, 0.f};
;                     if (has_prev) { e0 = *(const LAS f32x4*)(ex + ((slot * 2 + 0) * 256 + bj * HALF + cl0 + n * 16)); e1 = *(const LAS f32x4*)(ex + ((slot * 2 + 1) * 256 + bj * HALF + cl0 + n * 16)); }
;                     q1[bj] = e1;
; #pragma unroll
;                     for (int e = 0; e < 4; ++e) q2[bj][e] = (fr == 1) ? e1[e] : e0[e];
	v_pk_fma_f32 v[166:167], v[190:191], v[158:159], v[216:217]
	v_pk_fma_f32 v[164:165], v[196:197], v[132:133], v[164:165]
	v_pk_fma_f32 v[166:167], v[198:199], v[134:135], v[166:167]
	v_pk_fma_f32 v[164:165], v[48:49], v[204:205], v[164:165]
	v_pk_fma_f32 v[166:167], v[50:51], v[206:207], v[166:167]
	v_pk_fma_f32 v[168:169], v[192:193], v[160:161], v[218:219]
	v_pk_fma_f32 v[170:171], v[194:195], v[162:163], v[220:221]
	v_pk_fma_f32 v[168:169], v[200:201], v[136:137], v[168:169]
	v_pk_fma_f32 v[170:171], v[202:203], v[138:139], v[170:171]
	v_pk_fma_f32 v[168:169], v[32:33], v[210:211], v[168:169]
	v_pk_fma_f32 v[170:171], v[34:35], v[212:213], v[170:171]
	v_pk_mul_f32 v[132:133], v[164:165], s[28:29] op_sel_hi:[1,0]
	v_pk_mul_f32 v[134:135], v[166:167], s[28:29] op_sel_hi:[1,0]
	v_exp_f32_e32 v132, v132
	v_exp_f32_e32 v133, v133
	v_exp_f32_e32 v134, v134
	v_exp_f32_e32 v135, v135
	v_pk_add_f32 v[132:133], v[132:133], s[28:29] op_sel:[0,1] op_sel_hi:[1,1]
	v_pk_add_f32 v[134:135], v[134:135], s[28:29] op_sel:[0,1] op_sel_hi:[1,1]
	v_rcp_f32_e32 v132, v132
	v_rcp_f32_e32 v133, v133
	v_rcp_f32_e32 v134, v134
	v_rcp_f32_e32 v135, v135
	v_pk_mul_f32 v[164:165], v[164:165], v[132:133]
	v_pk_mul_f32 v[166:167], v[166:167], v[134:135]
	v_pk_mul_f32 v[164:165], v[164:165], v[168:169]
	v_pk_mul_f32 v[166:167], v[166:167], v[170:171]
	v_cvt_pk_bf16_f32 v164, v164, v165
	v_cvt_pk_bf16_f32 v165, v166, v167
	v_add_u32_e32 v181, 0x1b8000, v155
	global_store_dwordx2 v181, v[164:165], s[0:1] offset:32
	v_mov_b32_dpp v222, v8 row_shr:1 row_mask:0xf bank_mask:0xf
	v_mov_b32_dpp v223, v9 row_shr:1 row_mask:0xf bank_mask:0xf
	v_mov_b32_dpp v224, v10 row_shr:1 row_mask:0xf bank_mask:0xf
	v_mov_b32_dpp v225, v11 row_shr:1 row_mask:0xf bank_mask:0xf
	v_mov_b32_dpp v230, v8 row_shr:2 row_mask:0xf bank_mask:0xf
	v_mov_b32_dpp v231, v9 row_shr:2 row_mask:0xf bank_mask:0xf
	v_mov_b32_dpp v232, v10 row_shr:2 row_mask:0xf bank_mask:0xf
	v_mov_b32_dpp v233, v11 row_shr:2 row_mask:0xf bank_mask:0xf
	v_mov_b32_dpp v226, v0 row_shr:1 row_mask:0xf bank_mask:0xf
	v_mov_b32_dpp v227, v1 row_shr:1 row_mask:0xf bank_mask:0xf
	v_mov_b32_dpp v228, v2 row_shr:1 row_mask:0xf bank_mask:0xf
	v_mov_b32_dpp v229, v3 row_shr:1 row_mask:0xf bank_mask:0xf
	v_mov_b32_dpp v108, v0 row_shr:2 row_mask:0xf bank_mask:0xf
	v_mov_b32_dpp v109, v1 row_shr:2 row_mask:0xf bank_mask:0xf
	v_mov_b32_dpp v110, v2 row_shr:2 row_mask:0xf bank_mask:0xf
	v_mov_b32_dpp v111, v3 row_shr:2 row_mask:0xf bank_mask:0xf
	v_pk_fma_f32 v[164:165], v[188:189], v[230:231], v[214:215]
	v_pk_fma_f32 v[166:167], v[190:191], v[232:233], v[216:217]
	v_pk_fma_f32 v[164:165], v[196:197], v[222:223], v[164:165]
	v_pk_fma_f32 v[166:167], v[198:199], v[224:225], v[166:167]
	v_pk_fma_f32 v[164:165], v[8:9], v[204:205], v[164:165]
	v_pk_fma_f32 v[166:167], v[10:11], v[206:207], v[166:167]
	v_pk_fma_f32 v[168:169], v[192:193], v[108:109], v[218:219]
	v_pk_fma_f32 v[170:171], v[194:195], v[110:111], v[220:221]
	v_pk_fma_f32 v[168:169], v[200:201], v[226:227], v[168:169]
	v_pk_fma_f32 v[170:171], v[202:203], v[228:229], v[170:171]
	v_pk_fma_f32 v[168:169], v[0:1], v[210:211], v[168:169]
	v_pk_fma_f32 v[170:171], v[2:3], v[212:213], v[170:171]
	v_pk_mul_f32 v[222:223], v[164:165], s[28:29] op_sel_hi:[1,0]
	v_pk_mul_f32 v[224:225], v[166:167], s[28:29] op_sel_hi:[1,0]
	v_exp_f32_e32 v222, v222
	v_exp_f32_e32 v223, v223
	v_exp_f32_e32 v224, v224
	v_exp_f32_e32 v225, v225
	v_pk_add_f32 v[222:223], v[222:223], s[28:29] op_sel:[0,1] op_sel_hi:[1,1]
	v_pk_add_f32 v[224:225], v[224:225], s[28:29] op_sel:[0,1] op_sel_hi:[1,1]
	v_rcp_f32_e32 v222, v222
	v_rcp_f32_e32 v223, v223
	v_rcp_f32_e32 v224, v224
	v_rcp_f32_e32 v225, v225
	v_pk_mul_f32 v[164:165], v[164:165], v[222:223]
	v_pk_mul_f32 v[166:167], v[166:167], v[224:225]
	v_pk_mul_f32 v[164:165], v[164:165], v[168:169]
	v_pk_mul_f32 v[166:167], v[166:167], v[170:171]
	v_cvt_pk_bf16_f32 v164, v164, v165
	v_cvt_pk_bf16_f32 v165, v166, v167
	v_add_u32_e32 v181, 0x1e4000, v155
	global_store_dwordx2 v181, v[164:165], s[0:1] offset:32
	s_waitcnt lgkmcnt(0)
	s_barrier
	s_barrier
	s_cmp_lg_u32 s22, 0
	s_cselect_b32 s14, 0, 0xfffff800
	v_lshl_add_u32 v180, v154, 2, s66
	v_add_u32_e32 v180, s14, v180
	ds_read_b128 v[188:191], v153
	ds_read_b128 v[192:195], v153 offset:128
	ds_read_b128 v[196:199], v153 offset:256
	ds_read_b128 v[200:203], v153 offset:384
	ds_read_b128 v[204:207], v153 offset:512
	ds_read_b128 v[210:213], v153 offset:640
	ds_read_b128 v[214:217], v153 offset:768
	ds_read_b128 v[218:221], v153 offset:896
	s_cmp_lg_u32 s22, 0
	s_cbranch_scc1 .Lp6_b_00_prev
	v_mov_b32_e32 v222, 0
	v_mov_b32_e32 v223, 0
	v_mov_b32_e32 v224, 0
	v_mov_b32_e32 v225, 0
	v_mov_b32_e32 v226, 0
	v_mov_b32_e32 v227, 0
	v_mov_b32_e32 v228, 0
	v_mov_b32_e32 v229, 0
	v_mov_b32_e32 v230, 0
	v_mov_b32_e32 v231, 0
	v_mov_b32_e32 v232, 0
	v_mov_b32_e32 v233, 0
	v_mov_b32_e32 v108, 0
	v_mov_b32_e32 v109, 0
	v_mov_b32_e32 v110, 0
	v_mov_b32_e32 v111, 0
	s_branch .Lp6_b_00_go
